# bundle on v84: UP epilogue canonicalise trim (hazard-padded), attention prologue tile-1 load hoist, barrier non-leaders poll top-level generation
# baseline (speedup 1.0000x reference)
.LBB0_595:
	s_or_b64 exec, exec, s[4:5]
	s_mov_b64 s[4:5], exec
	v_mbcnt_lo_u32_b32 v0, s4, 0
	v_mbcnt_hi_u32_b32 v0, s5, v0
	v_cmp_eq_u32_e32 vcc, 0, v0
	s_waitcnt vmcnt(0)
	s_and_saveexec_b64 s[14:15], vcc
	s_cbranch_execz .LBB0_10
	s_bcnt1_i32_b64 s4, s[4:5]
	v_mov_b32_e32 v0, s4
	s_branch .LBB0_10
